# attention loop: waves 4-7 run the PV MFMAs of a step at the start of the next step (operands held in registers); prio 1 on waves 0-3
# baseline (speedup 1.0000x reference)
.LBB0_1340:
	s_and_b64 vcc, exec, s[0:1]
	s_cbranch_vccz .LBB0_1313
	s_mov_b32 s99, 0
	s_cmp_lt_i32 s26, 32
	s_cselect_b64 s[0:1], -1, 0
	s_cmp_gt_i32 s26, 31
	s_mov_b64 s[4:5], -1
	s_cbranch_scc1 .LBB0_1343
	s_and_b32 s27, s26, 7
	s_ashr_i32 s73, s26, 3
	s_mov_b64 s[4:5], 0

.LBB0_1377:
	s_and_b64 vcc, exec, s[0:1]
	s_waitcnt lgkmcnt(0)
	s_barrier
	s_cbranch_vccnz .LBB0_1402
	v_max_f32_e32 v66, v153, v153
	v_max_f32_e32 v67, v152, v152
	v_max_f32_e32 v66, v67, v66
	v_max3_f32 v66, v150, v151, v66
	v_mul_f32_e32 v67, 0x4f800000, v66
	v_cmp_gt_f32_e32 vcc, s38, v66
	v_max_f32_e32 v70, v148, v148
	s_add_i32 s6, s26, -6
	v_cndmask_b32_e32 v66, v66, v67, vcc
	v_sqrt_f32_e32 v67, v66
	s_mov_b32 s35, 5
	v_add_u32_e32 v68, -1, v67
	v_fma_f32 v69, -v68, v67, v66
	v_cmp_ge_f32_e64 s[0:1], 0, v69
	v_add_u32_e32 v69, 1, v67
	s_nop 0
	v_cndmask_b32_e64 v68, v67, v68, s[0:1]
	v_fma_f32 v67, -v69, v67, v66
	v_cmp_lt_f32_e64 s[0:1], 0, v67
	s_nop 1
	v_cndmask_b32_e64 v67, v68, v69, s[0:1]
	v_max_f32_e32 v69, v149, v149
	v_max_f32_e32 v69, v70, v69
	v_max3_f32 v69, v146, v147, v69
	v_mul_f32_e32 v70, 0x4f800000, v69
	v_cmp_gt_f32_e64 s[0:1], s38, v69
	v_mul_f32_e32 v68, 0x37800000, v67
	v_cndmask_b32_e32 v67, v67, v68, vcc
	v_cndmask_b32_e64 v70, v69, v70, s[0:1]
	v_sqrt_f32_e32 v69, v70
	v_cmp_class_f32_e32 vcc, v66, v213
	s_nop 1
	v_cndmask_b32_e32 v178, v67, v66, vcc
	v_add_u32_e32 v66, -1, v69
	v_fma_f32 v67, -v66, v69, v70
	v_cmp_ge_f32_e32 vcc, 0, v67
	v_add_u32_e32 v67, 1, v69
	v_fma_f32 v68, -v67, v69, v70
	v_cndmask_b32_e32 v66, v69, v66, vcc
	v_cmp_lt_f32_e32 vcc, 0, v68
	s_nop 1
	v_cndmask_b32_e32 v66, v66, v67, vcc
	v_mul_f32_e32 v67, 0x37800000, v66
	v_cndmask_b32_e64 v71, v66, v67, s[0:1]
	v_mov_b32_e32 v66, s39
	ds_read_b128 v[66:69], v66
	v_cmp_class_f32_e32 vcc, v70, v213
	s_add_i32 s0, 0, 0x11c20
	s_nop 0
	v_cndmask_b32_e32 v179, v71, v70, vcc
	v_mov_b32_e32 v70, s0
	ds_read_b128 v[70:73], v70
	s_waitcnt lgkmcnt(1)
	v_max_f32_e32 v69, v69, v69
	v_max_f32_e32 v68, v68, v68
	v_min_f32_e32 v68, v68, v69
	v_min3_f32 v67, v66, v67, v68
	s_waitcnt lgkmcnt(0)
	v_max_f32_e32 v66, v73, v73
	v_max_f32_e32 v68, v72, v72
	v_min_f32_e32 v66, v68, v66
	v_min3_f32 v66, v70, v71, v66
	s_mov_b32 s0, 0xc2200000
	v_pk_add_f32 v[180:181], v[66:67], s[0:1] op_sel_hi:[1,0]
	s_lshl_b32 s0, s26, 2
	s_add_i32 s0, s0, 0
	s_add_i32 s13, s0, 0x117e8
	s_lshl_b32 s0, s26, 6
	s_sub_i32 s12, 0, s0
	s_lshl_b32 s0, s26, 1
	s_sub_i32 s0, s71, s0
	v_mov_b32_e32 v200, v179
	s_add_i32 s34, s0, 8
	v_mov_b32_e32 v248, s13
	ds_read2_b32 v[248:249], v248 offset0:5 offset1:133
	s_cmp_eq_u32 s70, 0
	s_cselect_b64 vcc, -1, 0
	s_waitcnt lgkmcnt(0)
	v_mul_f32_e32 v248, v178, v248
	v_mul_f32_e32 v249, v179, v249
	v_cndmask_b32_e32 v248, v249, v248, vcc
	v_sub_f32_e32 v250, v226, v248
	v_exp_f32_e32 v250, v250
	v_mov_b32_e32 v226, v248
	s_nop 0
	v_mul_f32_e32 v224, v224, v250
	v_pk_mul_f32 v[2:3], v[2:3], v[250:251] op_sel_hi:[1,0]
	v_pk_mul_f32 v[4:5], v[4:5], v[250:251] op_sel_hi:[1,0]
	v_pk_mul_f32 v[6:7], v[6:7], v[250:251] op_sel_hi:[1,0]
	v_pk_mul_f32 v[8:9], v[8:9], v[250:251] op_sel_hi:[1,0]
	v_pk_mul_f32 v[10:11], v[10:11], v[250:251] op_sel_hi:[1,0]
	v_pk_mul_f32 v[12:13], v[12:13], v[250:251] op_sel_hi:[1,0]
	v_pk_mul_f32 v[14:15], v[14:15], v[250:251] op_sel_hi:[1,0]
	v_pk_mul_f32 v[16:17], v[16:17], v[250:251] op_sel_hi:[1,0]
	v_pk_mul_f32 v[18:19], v[18:19], v[250:251] op_sel_hi:[1,0]
	v_pk_mul_f32 v[20:21], v[20:21], v[250:251] op_sel_hi:[1,0]
	v_pk_mul_f32 v[22:23], v[22:23], v[250:251] op_sel_hi:[1,0]
	v_pk_mul_f32 v[24:25], v[24:25], v[250:251] op_sel_hi:[1,0]
	v_pk_mul_f32 v[26:27], v[26:27], v[250:251] op_sel_hi:[1,0]
	v_pk_mul_f32 v[28:29], v[28:29], v[250:251] op_sel_hi:[1,0]
	v_pk_mul_f32 v[30:31], v[30:31], v[250:251] op_sel_hi:[1,0]
	v_pk_mul_f32 v[32:33], v[32:33], v[250:251] op_sel_hi:[1,0]
	v_pk_mul_f32 v[34:35], v[34:35], v[250:251] op_sel_hi:[1,0]
	v_pk_mul_f32 v[36:37], v[36:37], v[250:251] op_sel_hi:[1,0]
	v_pk_mul_f32 v[38:39], v[38:39], v[250:251] op_sel_hi:[1,0]
	v_pk_mul_f32 v[40:41], v[40:41], v[250:251] op_sel_hi:[1,0]
	v_pk_mul_f32 v[42:43], v[42:43], v[250:251] op_sel_hi:[1,0]
	v_pk_mul_f32 v[44:45], v[44:45], v[250:251] op_sel_hi:[1,0]
	v_pk_mul_f32 v[46:47], v[46:47], v[250:251] op_sel_hi:[1,0]
	v_pk_mul_f32 v[48:49], v[48:49], v[250:251] op_sel_hi:[1,0]
	v_pk_mul_f32 v[50:51], v[50:51], v[250:251] op_sel_hi:[1,0]
	v_pk_mul_f32 v[52:53], v[52:53], v[250:251] op_sel_hi:[1,0]
	v_pk_mul_f32 v[54:55], v[54:55], v[250:251] op_sel_hi:[1,0]
	v_pk_mul_f32 v[56:57], v[56:57], v[250:251] op_sel_hi:[1,0]
	v_pk_mul_f32 v[58:59], v[58:59], v[250:251] op_sel_hi:[1,0]
	v_pk_mul_f32 v[60:61], v[60:61], v[250:251] op_sel_hi:[1,0]
	v_pk_mul_f32 v[62:63], v[62:63], v[250:251] op_sel_hi:[1,0]
	v_pk_mul_f32 v[64:65], v[64:65], v[250:251] op_sel_hi:[1,0]
	s_mov_b32 s99, 0
	s_branch .LBB0_1380

.LBB0_1380:
	s_cmp_eq_u32 s99, 2
	s_cbranch_scc0 .Ldefa_skip
	s_waitcnt lgkmcnt(0)
	v_mfma_f32_32x32x16_bf16 v[50:65], v[166:169], v[66:69], v[50:65]
	v_mfma_f32_32x32x16_bf16 v[34:49], v[170:173], v[66:69], v[34:49]
	v_mfma_f32_32x32x16_bf16 v[18:33], v[174:177], v[66:69], v[18:33]
	v_mfma_f32_32x32x16_bf16 v[2:17], v[162:165], v[66:69], v[2:17]
	v_mfma_f32_32x32x16_bf16 v[50:65], v[150:153], v[74:77], v[50:65]
	v_mfma_f32_32x32x16_bf16 v[34:49], v[154:157], v[74:77], v[34:49]
	v_mfma_f32_32x32x16_bf16 v[18:33], v[158:161], v[74:77], v[18:33]
	v_mfma_f32_32x32x16_bf16 v[2:17], v[146:149], v[74:77], v[2:17]
	v_mfma_f32_32x32x16_bf16 v[50:65], v[82:85], v[70:73], v[50:65]
	v_mfma_f32_32x32x16_bf16 v[34:49], v[90:93], v[70:73], v[34:49]
	v_mfma_f32_32x32x16_bf16 v[18:33], v[228:231], v[70:73], v[18:33]
	v_mfma_f32_32x32x16_bf16 v[2:17], v[236:239], v[70:73], v[2:17]
	v_mfma_f32_32x32x16_bf16 v[50:65], v[86:89], v[78:81], v[50:65]
	v_mfma_f32_32x32x16_bf16 v[34:49], v[94:97], v[78:81], v[34:49]
	v_mfma_f32_32x32x16_bf16 v[18:33], v[232:235], v[78:81], v[18:33]
	v_mfma_f32_32x32x16_bf16 v[2:17], v[240:243], v[78:81], v[2:17]
	s_mov_b32 s99, 0

.LBB0_1387:
	v_sub_f32_e32 v246, v226, v245
	v_sub_f32_e32 v78, v188, v246
	v_exp_f32_e32 v236, v78
	v_sub_f32_e32 v78, v233, v246
	v_exp_f32_e32 v237, v78
	v_sub_f32_e32 v78, v234, v246
	v_sub_f32_e32 v79, v235, v246
	v_exp_f32_e32 v78, v78
	v_exp_f32_e32 v188, v79
	v_add_f32_e32 v79, v236, v237
	v_sub_f32_e32 v86, v86, v246
	v_sub_f32_e32 v82, v82, v246
	v_pk_add_f32 v[80:81], v[78:79], v[188:189]
	v_sub_f32_e32 v79, v229, v246
	v_pk_add_f32 v[80:81], v[80:81], v[80:81] op_sel_hi:[0,1]
	v_sub_f32_e32 v80, v230, v246
	v_exp_f32_e32 v234, v80
	v_sub_f32_e32 v80, v231, v246
	v_exp_f32_e32 v79, v79
	v_exp_f32_e32 v90, v80
	v_sub_f32_e32 v80, v232, v246
	v_exp_f32_e32 v80, v80
	v_add_f32_e32 v91, v79, v234
	v_sub_f32_e32 v74, v74, v246
	v_sub_f32_e32 v70, v70, v246
	v_pk_add_f32 v[92:93], v[90:91], v[80:81]
	v_sub_f32_e32 v81, v184, v246
	v_pk_add_f32 v[92:93], v[92:93], v[92:93] op_sel_hi:[0,1]
	v_sub_f32_e32 v91, v185, v246
	v_sub_f32_e32 v92, v227, v246
	v_exp_f32_e32 v81, v81
	v_exp_f32_e32 v91, v91
	v_exp_f32_e32 v94, v92
	v_sub_f32_e32 v92, v228, v246
	v_exp_f32_e32 v92, v92
	v_add_f32_e32 v95, v81, v91
	v_sub_f32_e32 v66, v66, v246
	v_pk_add_f32 v[96:97], v[94:95], v[92:93]
	v_exp_f32_e32 v93, v86
	v_sub_f32_e32 v86, v87, v246
	v_pk_add_f32 v[96:97], v[96:97], v[96:97] op_sel_hi:[0,1]
	v_exp_f32_e32 v95, v86
	v_sub_f32_e32 v86, v88, v246
	v_sub_f32_e32 v87, v89, v246
	v_exp_f32_e32 v86, v86
	v_exp_f32_e32 v96, v87
	v_add_f32_e32 v87, v93, v95
	v_pk_add_f32 v[88:89], v[86:87], v[96:97]
	v_exp_f32_e32 v87, v82
	v_sub_f32_e32 v82, v83, v246
	v_pk_add_f32 v[88:89], v[88:89], v[88:89] op_sel_hi:[0,1]
	v_exp_f32_e32 v97, v82
	v_sub_f32_e32 v82, v84, v246
	v_sub_f32_e32 v83, v85, v246
	v_exp_f32_e32 v82, v82
	v_exp_f32_e32 v88, v83
	v_add_f32_e32 v83, v87, v97
	v_pk_add_f32 v[84:85], v[82:83], v[88:89]
	v_exp_f32_e32 v83, v74
	v_sub_f32_e32 v74, v75, v246
	v_exp_f32_e32 v89, v74
	v_sub_f32_e32 v74, v76, v246
	v_pk_add_f32 v[84:85], v[84:85], v[84:85] op_sel_hi:[0,1]
	v_exp_f32_e32 v76, v74
	v_sub_f32_e32 v74, v77, v246
	v_exp_f32_e32 v84, v74
	v_add_f32_e32 v77, v83, v89
	v_pk_add_f32 v[74:75], v[76:77], v[84:85]
	v_exp_f32_e32 v77, v70
	v_sub_f32_e32 v70, v71, v246
	v_exp_f32_e32 v85, v70
	v_sub_f32_e32 v70, v72, v246
	v_pk_add_f32 v[184:185], v[74:75], v[74:75] op_sel_hi:[0,1]
	v_exp_f32_e32 v228, v70
	v_sub_f32_e32 v70, v73, v246
	v_exp_f32_e32 v184, v70
	v_add_f32_e32 v229, v77, v85
	v_cvt_pk_bf16_f32 v72, v91, v92
	v_cvt_pk_bf16_f32 v73, v95, v96
	v_pk_add_f32 v[70:71], v[228:229], v[184:185]
	v_exp_f32_e32 v185, v66
	v_sub_f32_e32 v66, v67, v246
	v_exp_f32_e32 v227, v66
	v_sub_f32_e32 v66, v68, v246
	v_pk_add_f32 v[230:231], v[70:71], v[70:71] op_sel_hi:[0,1]
	v_exp_f32_e32 v232, v66
	v_sub_f32_e32 v66, v69, v246
	v_exp_f32_e32 v230, v66
	v_add_f32_e32 v233, v185, v227
	v_cvt_pk_bf16_f32 v68, v81, v94
	v_cvt_pk_bf16_f32 v69, v93, v86
	v_pk_add_f32 v[66:67], v[232:233], v[230:231]
	v_cvt_pk_bf16_f32 v70, v237, v188
	v_add_f32_e32 v66, v66, v67
	v_add_f32_e32 v224, v224, v66
	v_cvt_pk_bf16_f32 v66, v236, v78
	v_cvt_pk_bf16_f32 v67, v79, v90
	v_cvt_pk_bf16_f32 v71, v234, v80
	v_cvt_pk_bf16_f32 v74, v87, v82
	v_cvt_pk_bf16_f32 v75, v83, v76
	v_cvt_pk_bf16_f32 v76, v77, v228
	v_cvt_pk_bf16_f32 v77, v185, v232
	v_cvt_pk_bf16_f32 v78, v97, v88
	v_cvt_pk_bf16_f32 v79, v89, v84
	v_cvt_pk_bf16_f32 v80, v85, v184
	v_cvt_pk_bf16_f32 v81, v227, v230
	ds_read_b128 v[82:85], v221 offset:17472
	ds_read_b128 v[86:89], v221 offset:17504
	ds_read_b128 v[90:93], v221 offset:22080
	ds_read_b128 v[94:97], v221 offset:22112
	ds_read_b128 v[228:231], v221 offset:26688
	ds_read_b128 v[232:235], v221 offset:26720
	ds_read_b128 v[236:239], v221 offset:31296
	ds_read_b128 v[240:243], v221 offset:31328
	s_cmp_eq_u32 s70, 1
	s_cbranch_scc0 .Lpv1_now
	s_mov_b32 s99, 1
	s_branch .LBB0_1388
.Lpv1_now:
	v_mfma_f32_32x32x16_bf16 v[50:65], v[162:165], v[66:69], v[50:65]
	v_mfma_f32_32x32x16_bf16 v[34:49], v[166:169], v[66:69], v[34:49]
	v_mfma_f32_32x32x16_bf16 v[18:33], v[170:173], v[66:69], v[18:33]
	v_mfma_f32_32x32x16_bf16 v[2:17], v[174:177], v[66:69], v[2:17]
	v_mfma_f32_32x32x16_bf16 v[50:65], v[146:149], v[74:77], v[50:65]
	v_mfma_f32_32x32x16_bf16 v[34:49], v[150:153], v[74:77], v[34:49]
	v_mfma_f32_32x32x16_bf16 v[18:33], v[154:157], v[74:77], v[18:33]
	v_mfma_f32_32x32x16_bf16 v[2:17], v[158:161], v[74:77], v[2:17]
	s_waitcnt lgkmcnt(7)
	v_mfma_f32_32x32x16_bf16 v[50:65], v[82:85], v[70:73], v[50:65]
	s_waitcnt lgkmcnt(5)
	v_mfma_f32_32x32x16_bf16 v[34:49], v[90:93], v[70:73], v[34:49]
	s_waitcnt lgkmcnt(3)
	v_mfma_f32_32x32x16_bf16 v[18:33], v[228:231], v[70:73], v[18:33]
	s_waitcnt lgkmcnt(1)
	v_mfma_f32_32x32x16_bf16 v[2:17], v[236:239], v[70:73], v[2:17]
	v_mfma_f32_32x32x16_bf16 v[50:65], v[86:89], v[78:81], v[50:65]
	v_mfma_f32_32x32x16_bf16 v[34:49], v[94:97], v[78:81], v[34:49]
	v_mfma_f32_32x32x16_bf16 v[18:33], v[232:235], v[78:81], v[18:33]
	s_waitcnt lgkmcnt(0)
	v_mfma_f32_32x32x16_bf16 v[2:17], v[240:243], v[78:81], v[2:17]

.LBB0_1390:
	s_andn2_b64 vcc, exec, s[0:1]
	s_waitcnt lgkmcnt(0)
	s_barrier
	s_cbranch_vccnz .LBB0_1396
	s_cmp_eq_u32 s99, 1
	s_cbranch_scc0 .Ldefb_skip
	s_waitcnt lgkmcnt(0)
	v_mfma_f32_32x32x16_bf16 v[50:65], v[162:165], v[66:69], v[50:65]
	v_mfma_f32_32x32x16_bf16 v[34:49], v[166:169], v[66:69], v[34:49]
	v_mfma_f32_32x32x16_bf16 v[18:33], v[170:173], v[66:69], v[18:33]
	v_mfma_f32_32x32x16_bf16 v[2:17], v[174:177], v[66:69], v[2:17]
	v_mfma_f32_32x32x16_bf16 v[50:65], v[146:149], v[74:77], v[50:65]
	v_mfma_f32_32x32x16_bf16 v[34:49], v[150:153], v[74:77], v[34:49]
	v_mfma_f32_32x32x16_bf16 v[18:33], v[154:157], v[74:77], v[18:33]
	v_mfma_f32_32x32x16_bf16 v[2:17], v[158:161], v[74:77], v[2:17]
	v_mfma_f32_32x32x16_bf16 v[50:65], v[82:85], v[70:73], v[50:65]
	v_mfma_f32_32x32x16_bf16 v[34:49], v[90:93], v[70:73], v[34:49]
	v_mfma_f32_32x32x16_bf16 v[18:33], v[228:231], v[70:73], v[18:33]
	v_mfma_f32_32x32x16_bf16 v[2:17], v[236:239], v[70:73], v[2:17]
	v_mfma_f32_32x32x16_bf16 v[50:65], v[86:89], v[78:81], v[50:65]
	v_mfma_f32_32x32x16_bf16 v[34:49], v[94:97], v[78:81], v[34:49]
	v_mfma_f32_32x32x16_bf16 v[18:33], v[232:235], v[78:81], v[18:33]
	v_mfma_f32_32x32x16_bf16 v[2:17], v[240:243], v[78:81], v[2:17]
	s_mov_b32 s99, 0
.Ldefb_skip:
	v_mov_b32_e32 v248, s13
	ds_read2st64_b32 v[248:249], v248 offset1:2
	ds_read_b128 v[66:69], v222 offset:35840
	ds_read_b128 v[146:149], v222 offset:35872
	ds_read_b128 v[70:73], v222 offset:44544
	ds_read_b128 v[150:153], v222 offset:44576
	ds_read_b128 v[154:157], v222 offset:35904
	ds_read_b128 v[158:161], v222 offset:35936
	ds_read_b128 v[162:165], v222 offset:44608
	ds_read_b128 v[228:231], v222 offset:44640
	s_cmp_ge_i32 s35, s26
	s_cbranch_scc1 .LBB0_1397
	s_add_i32 s0, s12, s27
	s_addk_i32 s0, 0x180
	v_cvt_f32_i32_e32 v250, s0
	s_waitcnt lgkmcnt(8)
	v_mul_f32_e32 v252, v201, v250
	v_mov_b32_e32 v250, v248
	v_mov_b32_e32 v251, v249
	v_mov_b32_e32 v248, v252
	v_pk_fma_f32 v[248:249], v[178:179], v[250:251], v[248:249] op_sel_hi:[1,1,0] neg_lo:[0,0,1] neg_hi:[0,0,1]
	s_nop 0
	v_cmp_lt_f32_e32 vcc, v249, v181
	v_cmp_lt_f32_e64 s[0:1], v248, v180
	s_and_b64 s[0:1], s[0:1], vcc
	s_and_b64 vcc, exec, s[0:1]
	s_mov_b32 s0, s35
	s_cbranch_vccnz .LBB0_1394
	s_ashr_i32 s7, s6, 31
	s_lshl_b64 s[0:1], s[6:7], 14
	v_lshl_add_u64 v[250:251], v[196:197], 0, s[0:1]
	v_add_co_u32_e32 v252, vcc, 0x2000, v250
	v_lshl_add_u64 v[248:249], v[198:199], 0, s[0:1]
	s_nop 0
	v_addc_co_u32_e32 v253, vcc, 0, v251, vcc
	global_load_dwordx4 v[114:117], v[250:251], off
	global_load_dwordx4 v[118:121], v[252:253], off
	global_load_dwordx4 v[122:125], v[248:249], off
	v_add_co_u32_e32 v248, vcc, 0x2000, v248
	s_mov_b32 s0, s26
	s_nop 0
	v_addc_co_u32_e32 v249, vcc, 0, v249, vcc
	global_load_dwordx4 v[126:129], v[248:249], off

.LBB0_1400:
	v_sub_f32_e32 v246, v226, v245
	v_sub_f32_e32 v78, v188, v246
	v_exp_f32_e32 v236, v78
	v_sub_f32_e32 v78, v233, v246
	v_exp_f32_e32 v237, v78
	v_sub_f32_e32 v78, v234, v246
	v_sub_f32_e32 v79, v235, v246
	v_exp_f32_e32 v78, v78
	v_exp_f32_e32 v188, v79
	v_add_f32_e32 v79, v236, v237
	v_sub_f32_e32 v86, v86, v246
	v_sub_f32_e32 v82, v82, v246
	v_pk_add_f32 v[80:81], v[78:79], v[188:189]
	v_sub_f32_e32 v79, v229, v246
	v_pk_add_f32 v[80:81], v[80:81], v[80:81] op_sel_hi:[0,1]
	v_sub_f32_e32 v80, v230, v246
	v_exp_f32_e32 v234, v80
	v_sub_f32_e32 v80, v231, v246
	v_exp_f32_e32 v79, v79
	v_exp_f32_e32 v90, v80
	v_sub_f32_e32 v80, v232, v246
	v_exp_f32_e32 v80, v80
	v_add_f32_e32 v91, v79, v234
	v_sub_f32_e32 v74, v74, v246
	v_sub_f32_e32 v70, v70, v246
	v_pk_add_f32 v[92:93], v[90:91], v[80:81]
	v_sub_f32_e32 v81, v184, v246
	v_pk_add_f32 v[92:93], v[92:93], v[92:93] op_sel_hi:[0,1]
	v_sub_f32_e32 v91, v185, v246
	v_sub_f32_e32 v92, v227, v246
	v_exp_f32_e32 v81, v81
	v_exp_f32_e32 v91, v91
	v_exp_f32_e32 v94, v92
	v_sub_f32_e32 v92, v228, v246
	v_exp_f32_e32 v92, v92
	v_add_f32_e32 v95, v81, v91
	v_sub_f32_e32 v66, v66, v246
	v_pk_add_f32 v[96:97], v[94:95], v[92:93]
	v_exp_f32_e32 v93, v86
	v_sub_f32_e32 v86, v87, v246
	v_pk_add_f32 v[96:97], v[96:97], v[96:97] op_sel_hi:[0,1]
	v_exp_f32_e32 v95, v86
	v_sub_f32_e32 v86, v88, v246
	v_sub_f32_e32 v87, v89, v246
	v_exp_f32_e32 v86, v86
	v_exp_f32_e32 v96, v87
	v_add_f32_e32 v87, v93, v95
	v_pk_add_f32 v[88:89], v[86:87], v[96:97]
	v_exp_f32_e32 v87, v82
	v_sub_f32_e32 v82, v83, v246
	v_pk_add_f32 v[88:89], v[88:89], v[88:89] op_sel_hi:[0,1]
	v_exp_f32_e32 v97, v82
	v_sub_f32_e32 v82, v84, v246
	v_sub_f32_e32 v83, v85, v246
	v_exp_f32_e32 v82, v82
	v_exp_f32_e32 v88, v83
	v_add_f32_e32 v83, v87, v97
	v_pk_add_f32 v[84:85], v[82:83], v[88:89]
	v_exp_f32_e32 v83, v74
	v_sub_f32_e32 v74, v75, v246
	v_exp_f32_e32 v89, v74
	v_sub_f32_e32 v74, v76, v246
	v_pk_add_f32 v[84:85], v[84:85], v[84:85] op_sel_hi:[0,1]
	v_exp_f32_e32 v76, v74
	v_sub_f32_e32 v74, v77, v246
	v_exp_f32_e32 v84, v74
	v_add_f32_e32 v77, v83, v89
	v_pk_add_f32 v[74:75], v[76:77], v[84:85]
	v_exp_f32_e32 v77, v70
	v_sub_f32_e32 v70, v71, v246
	v_exp_f32_e32 v85, v70
	v_sub_f32_e32 v70, v72, v246
	v_pk_add_f32 v[184:185], v[74:75], v[74:75] op_sel_hi:[0,1]
	v_exp_f32_e32 v228, v70
	v_sub_f32_e32 v70, v73, v246
	v_exp_f32_e32 v184, v70
	v_add_f32_e32 v229, v77, v85
	v_cvt_pk_bf16_f32 v72, v91, v92
	v_cvt_pk_bf16_f32 v73, v95, v96
	v_pk_add_f32 v[70:71], v[228:229], v[184:185]
	v_exp_f32_e32 v185, v66
	v_sub_f32_e32 v66, v67, v246
	v_exp_f32_e32 v227, v66
	v_sub_f32_e32 v66, v68, v246
	v_pk_add_f32 v[230:231], v[70:71], v[70:71] op_sel_hi:[0,1]
	v_exp_f32_e32 v232, v66
	v_sub_f32_e32 v66, v69, v246
	v_exp_f32_e32 v230, v66
	v_add_f32_e32 v233, v185, v227
	v_cvt_pk_bf16_f32 v68, v81, v94
	v_cvt_pk_bf16_f32 v69, v93, v86
	v_pk_add_f32 v[66:67], v[232:233], v[230:231]
	v_cvt_pk_bf16_f32 v70, v237, v188
	v_add_f32_e32 v66, v66, v67
	v_add_f32_e32 v224, v224, v66
	v_cvt_pk_bf16_f32 v66, v236, v78
	v_cvt_pk_bf16_f32 v67, v79, v90
	v_cvt_pk_bf16_f32 v71, v234, v80
	v_cvt_pk_bf16_f32 v74, v87, v82
	v_cvt_pk_bf16_f32 v75, v83, v76
	v_cvt_pk_bf16_f32 v76, v77, v228
	v_cvt_pk_bf16_f32 v77, v185, v232
	v_cvt_pk_bf16_f32 v78, v97, v88
	v_cvt_pk_bf16_f32 v79, v89, v84
	v_cvt_pk_bf16_f32 v80, v85, v184
	v_cvt_pk_bf16_f32 v81, v227, v230
	ds_read_b128 v[82:85], v221 offset:53312
	ds_read_b128 v[86:89], v221 offset:53344
	ds_read_b128 v[90:93], v221 offset:57920
	ds_read_b128 v[94:97], v221 offset:57952
	ds_read_b128 v[228:231], v221 offset:62528
	ds_read_b128 v[232:235], v221 offset:62560
	ds_read_b128 v[236:239], v225 offset:13888
	ds_read_b128 v[240:243], v225 offset:13920
	s_cmp_eq_u32 s70, 1
	s_cbranch_scc0 .Lpv2_now
	s_mov_b32 s99, 2
	s_branch .Lh2_end
.Lpv2_now:
	v_mfma_f32_32x32x16_bf16 v[50:65], v[166:169], v[66:69], v[50:65]
	v_mfma_f32_32x32x16_bf16 v[34:49], v[170:173], v[66:69], v[34:49]
	v_mfma_f32_32x32x16_bf16 v[18:33], v[174:177], v[66:69], v[18:33]
	v_mfma_f32_32x32x16_bf16 v[2:17], v[162:165], v[66:69], v[2:17]
	v_mfma_f32_32x32x16_bf16 v[50:65], v[150:153], v[74:77], v[50:65]
	v_mfma_f32_32x32x16_bf16 v[34:49], v[154:157], v[74:77], v[34:49]
	v_mfma_f32_32x32x16_bf16 v[18:33], v[158:161], v[74:77], v[18:33]
	v_mfma_f32_32x32x16_bf16 v[2:17], v[146:149], v[74:77], v[2:17]
	s_waitcnt lgkmcnt(7)
	v_mfma_f32_32x32x16_bf16 v[50:65], v[82:85], v[70:73], v[50:65]
	s_waitcnt lgkmcnt(5)
	v_mfma_f32_32x32x16_bf16 v[34:49], v[90:93], v[70:73], v[34:49]
	s_waitcnt lgkmcnt(3)
	v_mfma_f32_32x32x16_bf16 v[18:33], v[228:231], v[70:73], v[18:33]
	s_waitcnt lgkmcnt(1)
	v_mfma_f32_32x32x16_bf16 v[2:17], v[236:239], v[70:73], v[2:17]
	v_mfma_f32_32x32x16_bf16 v[50:65], v[86:89], v[78:81], v[50:65]
	v_mfma_f32_32x32x16_bf16 v[34:49], v[94:97], v[78:81], v[34:49]
	v_mfma_f32_32x32x16_bf16 v[18:33], v[232:235], v[78:81], v[18:33]
	s_waitcnt lgkmcnt(0)
	v_mfma_f32_32x32x16_bf16 v[2:17], v[240:243], v[78:81], v[2:17]
.Lh2_end:
	s_cmp_ge_i32 s46, s26
	s_cbranch_scc1 .LBB0_1379
.LBB0_1401:
	s_cmp_lt_i32 s35, s26
	s_cbranch_scc0 .Latt_w3_drain
	s_waitcnt vmcnt(7)
	ds_write_b128 v195, v[98:101]
	s_waitcnt vmcnt(6)
	ds_write_b128 v195, v[102:105] offset:8704
	s_waitcnt vmcnt(5)
	ds_write_b128 v220, v[106:109] offset:17408
	s_waitcnt vmcnt(4)
	ds_write_b128 v220, v[110:113] offset:26624
	s_branch .LBB0_1379

.Lexit_def:
	s_cmp_eq_u32 s99, 1
	s_cbranch_scc0 .Ldefx1_skip
	s_waitcnt lgkmcnt(0)
	v_mfma_f32_32x32x16_bf16 v[50:65], v[162:165], v[66:69], v[50:65]
	v_mfma_f32_32x32x16_bf16 v[34:49], v[166:169], v[66:69], v[34:49]
	v_mfma_f32_32x32x16_bf16 v[18:33], v[170:173], v[66:69], v[18:33]
	v_mfma_f32_32x32x16_bf16 v[2:17], v[174:177], v[66:69], v[2:17]
	v_mfma_f32_32x32x16_bf16 v[50:65], v[146:149], v[74:77], v[50:65]
	v_mfma_f32_32x32x16_bf16 v[34:49], v[150:153], v[74:77], v[34:49]
	v_mfma_f32_32x32x16_bf16 v[18:33], v[154:157], v[74:77], v[18:33]
	v_mfma_f32_32x32x16_bf16 v[2:17], v[158:161], v[74:77], v[2:17]
	v_mfma_f32_32x32x16_bf16 v[50:65], v[82:85], v[70:73], v[50:65]
	v_mfma_f32_32x32x16_bf16 v[34:49], v[90:93], v[70:73], v[34:49]
	v_mfma_f32_32x32x16_bf16 v[18:33], v[228:231], v[70:73], v[18:33]
	v_mfma_f32_32x32x16_bf16 v[2:17], v[236:239], v[70:73], v[2:17]
	v_mfma_f32_32x32x16_bf16 v[50:65], v[86:89], v[78:81], v[50:65]
	v_mfma_f32_32x32x16_bf16 v[34:49], v[94:97], v[78:81], v[34:49]
	v_mfma_f32_32x32x16_bf16 v[18:33], v[232:235], v[78:81], v[18:33]
	v_mfma_f32_32x32x16_bf16 v[2:17], v[240:243], v[78:81], v[2:17]
	s_mov_b32 s99, 0

.Ldefx2_skip:
.LBB0_1402:
	v_cmp_eq_u32_e64 s[0:1], 0, v192
	v_cmp_gt_i32_e32 vcc, s40, v192
	s_and_saveexec_b64 s[6:7], vcc
	s_cbranch_execz .Lepi_nosgl
	v_readlane_b32 s60, v244, 44
	v_readlane_b32 s61, v244, 45
	s_nop 3
	v_lshl_add_u64 v[254:255], v[192:193], 2, s[60:61]
	global_load_dword v247, v[254:255], off
